# grid barriers: non-leader workgroups poll the top generation word directly (one hop fewer) and poll with s_sleep 1
# speedup vs baseline: 1.0233x; 1.0031x over previous
; __device__ __forceinline__ unsigned xb_ld(unsigned* p)              { return __hip_atomic_load(p, __ATOMIC_RELAXED, __HIP_MEMORY_SCOPE_AGENT); }
; __device__ __forceinline__ unsigned xb_add(unsigned* p, unsigned v) { return __hip_atomic_fetch_add(p, v, __ATOMIC_RELAXED, __HIP_MEMORY_SCOPE_AGENT); }
; #define XB_SPIN(cond, bar) do { unsigned _sp = 0; while (cond) { __builtin_amdgcn_s_sleep(6); \
;     if ((++_sp & 255u) == 0u) { if (xb_ld(&(bar)[XB_TMO])) break; if (_sp > XB_SPIN_CAP) { atomicAdd(&(bar)[XB_TMO], 1u); break; } } } } while (0)
; __device__ __forceinline__ void xcd_barrier(const XcdBarrier& b) {
;     ...
;         unsigned nloc = b.st[0], nx = b.st[1];
;         if (nloc == 0u) { xcd_barrier_complete(bar, b.x, nloc, nx); b.st[0] = nloc; b.st[1] = nx; }
;         const unsigned old = xb_add(&bar[XB_XSUB(b.x)], 1u);
;         const unsigned gen = old / nloc;
;         if (old + 1u == (gen + 1u) * nloc) {
;             __builtin_amdgcn_fence(__ATOMIC_RELEASE, "agent");
;             asm volatile("s_waitcnt vmcnt(0)" ::: "memory");
;             const unsigned og = xb_add(&bar[XB_TOP], 1u);
;             const unsigned tg = og / nx;
;             if (og + 1u == (tg + 1u) * nx) xb_add(&bar[XB_TOPGEN], 1u);
;             else XB_SPIN(xb_ld(&bar[XB_TOPGEN]) == tg, bar);
;             asm volatile("" ::: "memory");
;             xb_add(&bar[XB_XGEN(b.x)], 1u);
;             asm volatile("s_waitcnt vmcnt(0)" ::: "memory");
;         } else {
;             XB_SPIN(xb_ld(&bar[XB_XGEN(b.x)]) == gen, bar);
.LBB0_238:
	s_or_b64 exec, exec, s[30:31]
	v_cvt_f32_u32_e32 v134, v132
	s_waitcnt vmcnt(0)
	v_readfirstlane_b32 s1, v133
	v_sub_u32_e32 v133, 0, v132
	v_rcp_iflag_f32_e32 v134, v134
	v_add_u32_e32 v135, s1, v131
	v_mul_f32_e32 v134, 0x4f7ffffe, v134
	v_cvt_u32_f32_e32 v134, v134
	v_mul_lo_u32 v131, v133, v134
	v_mul_hi_u32 v131, v134, v131
	v_add_u32_e32 v131, v134, v131
	v_mul_hi_u32 v131, v135, v131
	v_mul_lo_u32 v133, v131, v132
	v_sub_u32_e32 v133, v135, v133
	v_add_u32_e32 v134, 1, v131
	v_cmp_ge_u32_e32 vcc, v133, v132
	s_nop 1
	v_cndmask_b32_e32 v131, v131, v134, vcc
	v_sub_u32_e32 v134, v133, v132
	v_cndmask_b32_e32 v133, v133, v134, vcc
	v_add_u32_e32 v134, 1, v131
	v_cmp_ge_u32_e32 vcc, v133, v132
	v_add_u32_e32 v133, 1, v135
	s_nop 0
	v_cndmask_b32_e32 v131, v131, v134, vcc
	v_mul_lo_u32 v134, v132, v131
	v_add_u32_e32 v132, v134, v132
	v_cmp_ne_u32_e32 vcc, v133, v132
	s_and_saveexec_b64 s[14:15], vcc
	s_xor_b64 s[14:15], exec, s[14:15]
	s_cbranch_execz .LBB0_252
	s_waitcnt lgkmcnt(0)
	s_getpc_b64 s[34:35]
	s_add_u32 s34, s34, g_ctl@rel32@lo+29956
	s_addc_u32 s35, s35, g_ctl@rel32@hi+29964
	v_mov_b32_e32 v130, 0
	global_load_dword v130, v130, s[34:35] sc1
	s_waitcnt vmcnt(0)
	v_cmp_eq_u32_e32 vcc, v130, v131
	s_and_saveexec_b64 s[30:31], vcc
	s_cbranch_execz .LBB0_251
	s_mov_b32 s1, 1
	s_mov_b64 s[36:37], 0
	v_mov_b32_e32 v130, 0
	s_branch .LBB0_242

.LBB0_242:
	s_and_b32 s2, s1, 0xff
	s_mov_b64 s[40:41], -1
	s_cmp_lg_u32 s2, 0
	s_mov_b64 s[44:45], -1
	s_sleep 1
	s_cbranch_scc0 .LBB0_245
	s_and_b64 vcc, exec, s[44:45]
	s_cbranch_vccz .LBB0_241

; __device__ __forceinline__ unsigned xb_ld(unsigned* p)              { return __hip_atomic_load(p, __ATOMIC_RELAXED, __HIP_MEMORY_SCOPE_AGENT); }
; #define XB_SPIN(cond, bar) do { unsigned _sp = 0; while (cond) { __builtin_amdgcn_s_sleep(6); \
;     if ((++_sp & 255u) == 0u) { if (xb_ld(&(bar)[XB_TMO])) break; if (_sp > XB_SPIN_CAP) { atomicAdd(&(bar)[XB_TMO], 1u); break; } } } } while (0)
; __device__ __forceinline__ void xcd_barrier(const XcdBarrier& b) {
;     ...
;             else XB_SPIN(xb_ld(&bar[XB_TOPGEN]) == tg, bar);
.LBB0_259:
	s_and_b32 s2, s1, 0xff
	s_cmp_lg_u32 s2, 0
	s_mov_b64 s[40:41], -1
	s_sleep 1
	s_cbranch_scc0 .LBB0_262
	s_mov_b64 s[42:43], -1
	s_and_b64 vcc, exec, s[40:41]
	s_cbranch_vccz .LBB0_258

; __device__ __forceinline__ unsigned xb_ld(unsigned* p)              { return __hip_atomic_load(p, __ATOMIC_RELAXED, __HIP_MEMORY_SCOPE_AGENT); }
; __device__ __forceinline__ unsigned xb_add(unsigned* p, unsigned v) { return __hip_atomic_fetch_add(p, v, __ATOMIC_RELAXED, __HIP_MEMORY_SCOPE_AGENT); }
; #define XB_SPIN(cond, bar) do { unsigned _sp = 0; while (cond) { __builtin_amdgcn_s_sleep(6); \
;     if ((++_sp & 255u) == 0u) { if (xb_ld(&(bar)[XB_TMO])) break; if (_sp > XB_SPIN_CAP) { atomicAdd(&(bar)[XB_TMO], 1u); break; } } } } while (0)
; __device__ __forceinline__ void xcd_barrier(const XcdBarrier& b) {
;     ...
;         unsigned nloc = b.st[0], nx = b.st[1];
;         if (nloc == 0u) { xcd_barrier_complete(bar, b.x, nloc, nx); b.st[0] = nloc; b.st[1] = nx; }
;         const unsigned old = xb_add(&bar[XB_XSUB(b.x)], 1u);
;         const unsigned gen = old / nloc;
;         if (old + 1u == (gen + 1u) * nloc) {
;             __builtin_amdgcn_fence(__ATOMIC_RELEASE, "agent");
;             asm volatile("s_waitcnt vmcnt(0)" ::: "memory");
;             const unsigned og = xb_add(&bar[XB_TOP], 1u);
;             const unsigned tg = og / nx;
;             if (og + 1u == (tg + 1u) * nx) xb_add(&bar[XB_TOPGEN], 1u);
;             else XB_SPIN(xb_ld(&bar[XB_TOPGEN]) == tg, bar);
;             asm volatile("" ::: "memory");
;             xb_add(&bar[XB_XGEN(b.x)], 1u);
;             asm volatile("s_waitcnt vmcnt(0)" ::: "memory");
;         } else {
;             XB_SPIN(xb_ld(&bar[XB_XGEN(b.x)]) == gen, bar);
.LBB0_911:
	s_or_b64 exec, exec, s[10:11]
	v_cvt_f32_u32_e32 v6, v4
	s_waitcnt vmcnt(0)
	v_readfirstlane_b32 s0, v5
	v_sub_u32_e32 v5, 0, v4
	v_rcp_iflag_f32_e32 v6, v6
	v_add_u32_e32 v7, s0, v3
	v_mul_f32_e32 v6, 0x4f7ffffe, v6
	v_cvt_u32_f32_e32 v6, v6
	v_mul_lo_u32 v3, v5, v6
	v_mul_hi_u32 v3, v6, v3
	v_add_u32_e32 v3, v6, v3
	v_mul_hi_u32 v3, v7, v3
	v_mul_lo_u32 v5, v3, v4
	v_sub_u32_e32 v5, v7, v5
	v_add_u32_e32 v6, 1, v3
	v_cmp_ge_u32_e32 vcc, v5, v4
	s_nop 1
	v_cndmask_b32_e32 v3, v3, v6, vcc
	v_sub_u32_e32 v6, v5, v4
	v_cndmask_b32_e32 v5, v5, v6, vcc
	v_add_u32_e32 v6, 1, v3
	v_cmp_ge_u32_e32 vcc, v5, v4
	v_add_u32_e32 v5, 1, v7
	s_nop 0
	v_cndmask_b32_e32 v3, v3, v6, vcc
	v_mul_lo_u32 v6, v4, v3
	v_add_u32_e32 v4, v6, v4
	v_cmp_ne_u32_e32 vcc, v5, v4
	s_and_saveexec_b64 s[0:1], vcc
	s_xor_b64 s[8:9], exec, s[0:1]
	s_cbranch_execz .LBB0_925
	s_waitcnt lgkmcnt(0)
	s_getpc_b64 s[14:15]
	s_add_u32 s14, s14, g_ctl@rel32@lo+29956
	s_addc_u32 s15, s15, g_ctl@rel32@hi+29964
	v_mov_b32_e32 v2, 0
	global_load_dword v2, v2, s[14:15] sc1
	s_waitcnt vmcnt(0)
	v_cmp_eq_u32_e32 vcc, v2, v3
	s_and_saveexec_b64 s[10:11], vcc
	s_cbranch_execz .LBB0_924
	s_mov_b32 s0, 1
	s_mov_b64 s[24:25], 0
	v_mov_b32_e32 v2, 0
	s_branch .LBB0_915

.LBB0_915:
	s_and_b32 s1, s0, 0xff
	s_mov_b64 s[30:31], -1
	s_cmp_lg_u32 s1, 0
	s_mov_b64 s[36:37], -1
	s_sleep 1
	s_cbranch_scc0 .LBB0_918
	s_and_b64 vcc, exec, s[36:37]
	s_cbranch_vccz .LBB0_914

; __device__ __forceinline__ unsigned xb_ld(unsigned* p)              { return __hip_atomic_load(p, __ATOMIC_RELAXED, __HIP_MEMORY_SCOPE_AGENT); }
; #define XB_SPIN(cond, bar) do { unsigned _sp = 0; while (cond) { __builtin_amdgcn_s_sleep(6); \
;     if ((++_sp & 255u) == 0u) { if (xb_ld(&(bar)[XB_TMO])) break; if (_sp > XB_SPIN_CAP) { atomicAdd(&(bar)[XB_TMO], 1u); break; } } } } while (0)
; __device__ __forceinline__ void xcd_barrier(const XcdBarrier& b) {
;     ...
;             else XB_SPIN(xb_ld(&bar[XB_TOPGEN]) == tg, bar);
.LBB0_932:
	s_and_b32 s1, s0, 0xff
	s_cmp_lg_u32 s1, 0
	s_mov_b64 s[30:31], -1
	s_sleep 1
	s_cbranch_scc0 .LBB0_935
	s_mov_b64 s[34:35], -1
	s_and_b64 vcc, exec, s[30:31]
	s_cbranch_vccz .LBB0_931

; __device__ __forceinline__ unsigned xb_ld(unsigned* p)              { return __hip_atomic_load(p, __ATOMIC_RELAXED, __HIP_MEMORY_SCOPE_AGENT); }
; __device__ __forceinline__ unsigned xb_add(unsigned* p, unsigned v) { return __hip_atomic_fetch_add(p, v, __ATOMIC_RELAXED, __HIP_MEMORY_SCOPE_AGENT); }
; #define XB_SPIN(cond, bar) do { unsigned _sp = 0; while (cond) { __builtin_amdgcn_s_sleep(6); \
;     if ((++_sp & 255u) == 0u) { if (xb_ld(&(bar)[XB_TMO])) break; if (_sp > XB_SPIN_CAP) { atomicAdd(&(bar)[XB_TMO], 1u); break; } } } } while (0)
; __device__ __forceinline__ void xcd_barrier(const XcdBarrier& b) {
;     ...
;         unsigned nloc = b.st[0], nx = b.st[1];
;         if (nloc == 0u) { xcd_barrier_complete(bar, b.x, nloc, nx); b.st[0] = nloc; b.st[1] = nx; }
;         const unsigned old = xb_add(&bar[XB_XSUB(b.x)], 1u);
;         const unsigned gen = old / nloc;
;         if (old + 1u == (gen + 1u) * nloc) {
;             __builtin_amdgcn_fence(__ATOMIC_RELEASE, "agent");
;             asm volatile("s_waitcnt vmcnt(0)" ::: "memory");
;             const unsigned og = xb_add(&bar[XB_TOP], 1u);
;             const unsigned tg = og / nx;
;             if (og + 1u == (tg + 1u) * nx) xb_add(&bar[XB_TOPGEN], 1u);
;             else XB_SPIN(xb_ld(&bar[XB_TOPGEN]) == tg, bar);
;             asm volatile("" ::: "memory");
;             xb_add(&bar[XB_XGEN(b.x)], 1u);
;             asm volatile("s_waitcnt vmcnt(0)" ::: "memory");
;         } else {
;             XB_SPIN(xb_ld(&bar[XB_XGEN(b.x)]) == gen, bar);
.LBB0_1008:
	s_or_b64 exec, exec, s[8:9]
	v_cvt_f32_u32_e32 v6, v4
	s_waitcnt vmcnt(0)
	v_readfirstlane_b32 s2, v5
	v_sub_u32_e32 v5, 0, v4
	v_rcp_iflag_f32_e32 v6, v6
	v_add_u32_e32 v7, s2, v3
	v_mul_f32_e32 v6, 0x4f7ffffe, v6
	v_cvt_u32_f32_e32 v6, v6
	v_mul_lo_u32 v3, v5, v6
	v_mul_hi_u32 v3, v6, v3
	v_add_u32_e32 v3, v6, v3
	v_mul_hi_u32 v3, v7, v3
	v_mul_lo_u32 v5, v3, v4
	v_sub_u32_e32 v5, v7, v5
	v_add_u32_e32 v6, 1, v3
	v_cmp_ge_u32_e32 vcc, v5, v4
	s_nop 1
	v_cndmask_b32_e32 v3, v3, v6, vcc
	v_sub_u32_e32 v6, v5, v4
	v_cndmask_b32_e32 v5, v5, v6, vcc
	v_add_u32_e32 v6, 1, v3
	v_cmp_ge_u32_e32 vcc, v5, v4
	v_add_u32_e32 v5, 1, v7
	s_nop 0
	v_cndmask_b32_e32 v3, v3, v6, vcc
	v_mul_lo_u32 v6, v4, v3
	v_add_u32_e32 v4, v6, v4
	v_cmp_ne_u32_e32 vcc, v5, v4
	s_and_saveexec_b64 s[6:7], vcc
	s_xor_b64 s[6:7], exec, s[6:7]
	s_cbranch_execz .LBB0_1022
	s_waitcnt lgkmcnt(0)
	s_getpc_b64 s[10:11]
	s_add_u32 s10, s10, g_ctl@rel32@lo+29956
	s_addc_u32 s11, s11, g_ctl@rel32@hi+29964
	v_mov_b32_e32 v2, 0
	global_load_dword v2, v2, s[10:11] sc1
	s_waitcnt vmcnt(0)
	v_cmp_eq_u32_e32 vcc, v2, v3
	s_and_saveexec_b64 s[8:9], vcc
	s_cbranch_execz .LBB0_1021
	s_mov_b32 s2, 1
	s_mov_b64 s[14:15], 0
	v_mov_b32_e32 v2, 0
	s_branch .LBB0_1012

.LBB0_1012:
	s_and_b32 s20, s2, 0xff
	s_mov_b64 s[18:19], -1
	s_cmp_lg_u32 s20, 0
	s_mov_b64 s[22:23], -1
	s_sleep 1
	s_cbranch_scc0 .LBB0_1015
	s_and_b64 vcc, exec, s[22:23]
	s_cbranch_vccz .LBB0_1011

; __device__ __forceinline__ unsigned xb_ld(unsigned* p)              { return __hip_atomic_load(p, __ATOMIC_RELAXED, __HIP_MEMORY_SCOPE_AGENT); }
; #define XB_SPIN(cond, bar) do { unsigned _sp = 0; while (cond) { __builtin_amdgcn_s_sleep(6); \
;     if ((++_sp & 255u) == 0u) { if (xb_ld(&(bar)[XB_TMO])) break; if (_sp > XB_SPIN_CAP) { atomicAdd(&(bar)[XB_TMO], 1u); break; } } } } while (0)
; __device__ __forceinline__ void xcd_barrier(const XcdBarrier& b) {
;     ...
;             else XB_SPIN(xb_ld(&bar[XB_TOPGEN]) == tg, bar);
.LBB0_1029:
	s_and_b32 s16, s2, 0xff
	s_cmp_lg_u32 s16, 0
	s_mov_b64 s[18:19], -1
	s_sleep 1
	s_cbranch_scc0 .LBB0_1032
	s_mov_b64 s[20:21], -1
	s_and_b64 vcc, exec, s[18:19]
	s_cbranch_vccz .LBB0_1028
